# same as previous but only the last 4 k-blocks of w_in moved to the FFN1-gu tail
# baseline (speedup 1.0000x reference)
.LBB0_29:
	v_mov_b32_e32 v16, v183
	s_cmpk_gt_i32 s4, 0x2f7b
	v_readfirstlane_b32 s3, v16
	s_cbranch_scc1 .LBB0_427
	s_cmpk_lt_i32 s4, 0xb00
	s_mov_b32 s5, 1
	s_cbranch_scc1 .LBB0_34
	s_cmpk_gt_u32 s4, 0x15ff
	s_cbranch_scc0 .LBB0_35
	v_readlane_b32 s16, v234, 40
	v_readlane_b32 s22, v234, 46
	v_readlane_b32 s23, v234, 47
	v_readlane_b32 s24, v234, 48
	v_readlane_b32 s25, v234, 49
	s_add_i32 s12, s4, 0xffffea00
	v_readlane_b32 s17, v234, 41
	v_readlane_b32 s18, v234, 42
	v_readlane_b32 s19, v234, 43
	v_readlane_b32 s20, v234, 44
	v_readlane_b32 s21, v234, 45
	v_readlane_b32 s26, v234, 50
	v_readlane_b32 s27, v234, 51
	v_readlane_b32 s28, v234, 52
	v_readlane_b32 s29, v234, 53
	v_readlane_b32 s30, v234, 54
	v_readlane_b32 s31, v234, 55
	s_mov_b64 s[8:9], s[22:23]
	s_mov_b64 s[10:11], s[24:25]
	s_cbranch_execz .LBB0_36
	s_mov_b64 s[6:7], 0x4400000
	s_movk_i32 s28, 0x3a28
	s_mov_b32 s5, 3
	s_branch .LBB0_37

.LBB0_79:
	s_add_i32 s41, s4, s50
	s_cmpk_lt_i32 s41, 0x2f7c
	s_cselect_b64 s[10:11], -1, 0
	s_cmpk_gt_i32 s41, 0x2f7b
	s_cselect_b64 s[8:9], -1, 0
	s_and_b64 vcc, exec, s[8:9]
	s_mov_b64 s[12:13], s[6:7]
	s_mov_b32 s42, s28
	s_mov_b32 s43, s5
	s_mov_b32 s44, s2
	s_mov_b32 s45, s29
	s_cbranch_vccnz .LBB0_121
	s_cmpk_lt_i32 s41, 0xb00
	s_cbranch_scc1 .LBB0_84
	s_cmpk_gt_u32 s41, 0x15ff
	s_cbranch_scc0 .LBB0_85
	v_readlane_b32 s12, v234, 40
	v_readlane_b32 s14, v234, 42
	v_readlane_b32 s15, v234, 43
	v_readlane_b32 s16, v234, 44
	v_readlane_b32 s17, v234, 45
	v_readlane_b32 s18, v234, 46
	v_readlane_b32 s19, v234, 47
	v_readlane_b32 s20, v234, 48
	v_readlane_b32 s21, v234, 49
	s_add_i32 s3, s41, 0xffffea00
	v_readlane_b32 s13, v234, 41
	v_readlane_b32 s22, v234, 50
	v_readlane_b32 s23, v234, 51
	v_readlane_b32 s24, v234, 52
	v_readlane_b32 s25, v234, 53
	v_readlane_b32 s26, v234, 54
	v_readlane_b32 s27, v234, 55
	s_mov_b64 s[14:15], s[18:19]
	s_mov_b64 s[16:17], s[20:21]
	s_cbranch_execz .LBB0_86
	s_mov_b64 s[12:13], 0x4400000
	s_movk_i32 s42, 0x3a28
	s_mov_b32 s43, 3
	s_branch .LBB0_87

.LBB0_511:
	v_readlane_b32 s0, v234, 12
	v_writelane_b32 v233, s52, 12
	s_abs_i32 s52, s0
	v_cvt_f32_u32_e32 v0, s52
	s_sub_i32 s0, 0, s52
	v_readlane_b32 s1, v234, 13
	v_writelane_b32 v233, s50, 13
	v_rcp_iflag_f32_e32 v0, v0
	s_nop 0
	v_writelane_b32 v233, s51, 14
	v_mul_f32_e32 v0, 0x4f7ffffe, v0
	v_cvt_u32_f32_e32 v0, v0
	s_nop 0
	v_readfirstlane_b32 s53, v0
	s_mul_i32 s0, s0, s53
	s_mul_hi_u32 s0, s53, s0
	s_add_i32 s53, s53, s0
	s_mul_hi_u32 s0, s53, 0x5ac
	s_mul_i32 s0, s0, s52
	s_sub_i32 s0, 0x5ac, s0
	s_sub_i32 s1, s0, s52
	s_cmp_ge_u32 s0, s52
	s_cselect_b32 s0, s1, s0
	s_sub_i32 s1, s0, s52
	s_cmp_ge_u32 s0, s52
	s_cselect_b32 s5, s1, s0
	s_cmp_eq_u32 s5, 0
	s_cselect_b64 s[0:1], -1, 0
	s_cmp_lt_i32 s4, s5
	s_cselect_b64 s[2:3], -1, 0
	s_or_b64 s[0:1], s[0:1], s[2:3]
	s_and_b64 vcc, exec, s[0:1]
	s_cbranch_vccnz .LBB0_931
	v_readlane_b32 s2, v234, 14
	v_readlane_b32 s3, v234, 12
	v_readfirstlane_b32 s0, v183
	s_sub_i32 s2, s2, s5
	s_sub_i32 s3, s3, s5
	s_lshl_b32 s2, s2, 3
	s_lshr_b32 s0, s0, 6
	s_add_i32 s4, s2, s0
	s_lshl_b32 s33, s3, 3
	s_cmp_ge_u32 s4, 0xea4
	s_cbranch_scc1 .LBB0_931
	v_readlane_b32 s30, v234, 2
	v_readlane_b32 s31, v234, 3
	v_and_b32_e32 v176, 7, v183
	v_bfe_u32 v185, v183, 3, 3
	v_lshlrev_b32_e32 v177, 4, v185
	v_lshlrev_b32_e32 v186, 4, v176
	s_cmp_lt_u32 s4, 0xea4
	s_cbranch_scc1 .Lcv1_p0_go
	s_mov_b32 s22, 0
	s_branch .Lcv1_p0_end

.Lcv1_p0_seg1:
	s_add_u32 s34, s4, 0xe7c
	s_mul_i32 s39, s34, 18002
	s_lshr_b32 s39, s39, 22
	s_mul_i32 s40, s39, 233
	s_sub_u32 s40, s34, s40
	v_readlane_b32 s0, v234, 48
	v_readlane_b32 s1, v234, 49
	s_mul_i32 s2, s39, 0x3a2800
	s_lshl_b32 s3, s40, 8
	s_add_u32 s2, s2, s3
	s_add_u32 s0, s0, s2
	s_addc_u32 s1, s1, 0
	s_mov_b32 s41, 0xe8a0
	s_mov_b32 s42, 0x74500
	s_lshl_b32 s2, s40, 18
	s_lshl_b32 s3, s39, 7
	s_add_u32 s2, s2, s3
	s_add_u32 s2, s2, 0x43d8000
	s_add_u32 s16, s30, s2
	s_addc_u32 s17, s31, 0
	s_mov_b32 s20, 0x1000
	s_mov_b32 s21, 0x4000
	s_lshl_b32 s23, s40, 6
	s_mov_b64 s[46:47], -1
	s_cmp_eq_u32 s40, 232
	s_cbranch_scc0 .Lcv1_p0_full1
	s_mov_b64 s[46:47], 0xffff

.Lcv1_p0_end:
	s_cmp_lt_u32 s4, 0xea4
	s_cbranch_scc1 .Lcv1_p1_go
	s_mov_b32 s28, 0
	s_branch .Lcv1_p1_end

.Lcv1_p1_seg1:
	s_add_u32 s34, s4, 0xe7c
	s_mul_i32 s39, s34, 18002
	s_lshr_b32 s39, s39, 22
	s_mul_i32 s40, s39, 233
	s_sub_u32 s40, s34, s40
	v_readlane_b32 s0, v234, 48
	v_readlane_b32 s1, v234, 49
	s_mul_i32 s2, s39, 0x3a2800
	s_lshl_b32 s3, s40, 8
	s_add_u32 s2, s2, s3
	s_add_u32 s0, s0, s2
	s_addc_u32 s1, s1, 0
	s_mov_b32 s41, 0xe8a0
	s_mov_b32 s42, 0x74500
	s_lshl_b32 s2, s40, 18
	s_lshl_b32 s3, s39, 7
	s_add_u32 s2, s2, s3
	s_add_u32 s2, s2, 0x43d8000
	s_add_u32 s24, s30, s2
	s_addc_u32 s25, s31, 0
	s_mov_b32 s26, 0x1000
	s_mov_b32 s27, 0x4000
	s_lshl_b32 s29, s40, 6
	s_mov_b64 s[46:47], -1
	s_cmp_eq_u32 s40, 232
	s_cbranch_scc0 .Lcv1_p1_full1
	s_mov_b64 s[46:47], 0xffff

.Lcv1_pa_plain:
	v_pk_mul_f32 v[0:1], v[0:1], v[128:129] op_sel_hi:[1,0]
	v_pk_mul_f32 v[2:3], v[2:3], v[128:129] op_sel_hi:[1,0]
	v_pk_mul_f32 v[4:5], v[4:5], v[128:129] op_sel_hi:[1,0]
	v_pk_mul_f32 v[6:7], v[6:7], v[128:129] op_sel_hi:[1,0]
	v_pk_mul_f32 v[8:9], v[8:9], v[128:129] op_sel:[0,1]
	v_pk_mul_f32 v[10:11], v[10:11], v[128:129] op_sel:[0,1]
	v_pk_mul_f32 v[12:13], v[12:13], v[128:129] op_sel:[0,1]
	v_pk_mul_f32 v[14:15], v[14:15], v[128:129] op_sel:[0,1]
	v_pk_mul_f32 v[16:17], v[16:17], v[130:131] op_sel_hi:[1,0]
	v_pk_mul_f32 v[18:19], v[18:19], v[130:131] op_sel_hi:[1,0]
	v_pk_mul_f32 v[20:21], v[20:21], v[130:131] op_sel_hi:[1,0]
	v_pk_mul_f32 v[22:23], v[22:23], v[130:131] op_sel_hi:[1,0]
	v_pk_mul_f32 v[24:25], v[24:25], v[130:131] op_sel:[0,1]
	v_pk_mul_f32 v[26:27], v[26:27], v[130:131] op_sel:[0,1]
	v_pk_mul_f32 v[28:29], v[28:29], v[130:131] op_sel:[0,1]
	v_pk_mul_f32 v[30:31], v[30:31], v[130:131] op_sel:[0,1]
	v_pk_mul_f32 v[32:33], v[32:33], v[132:133] op_sel_hi:[1,0]
	v_pk_mul_f32 v[34:35], v[34:35], v[132:133] op_sel_hi:[1,0]
	v_pk_mul_f32 v[36:37], v[36:37], v[132:133] op_sel_hi:[1,0]
	v_pk_mul_f32 v[38:39], v[38:39], v[132:133] op_sel_hi:[1,0]
	v_pk_mul_f32 v[40:41], v[40:41], v[132:133] op_sel:[0,1]
	v_pk_mul_f32 v[42:43], v[42:43], v[132:133] op_sel:[0,1]
	v_pk_mul_f32 v[44:45], v[44:45], v[132:133] op_sel:[0,1]
	v_pk_mul_f32 v[46:47], v[46:47], v[132:133] op_sel:[0,1]
	v_pk_mul_f32 v[48:49], v[48:49], v[134:135] op_sel_hi:[1,0]
	v_pk_mul_f32 v[50:51], v[50:51], v[134:135] op_sel_hi:[1,0]
	v_pk_mul_f32 v[52:53], v[52:53], v[134:135] op_sel_hi:[1,0]
	v_pk_mul_f32 v[54:55], v[54:55], v[134:135] op_sel_hi:[1,0]
	v_pk_mul_f32 v[56:57], v[56:57], v[134:135] op_sel:[0,1]
	v_pk_mul_f32 v[58:59], v[58:59], v[134:135] op_sel:[0,1]
	v_pk_mul_f32 v[60:61], v[60:61], v[134:135] op_sel:[0,1]
	v_pk_mul_f32 v[62:63], v[62:63], v[134:135] op_sel:[0,1]
	v_cvt_pk_bf16_f32 v144, v0, v8
	v_cvt_pk_bf16_f32 v145, v16, v24
	v_cvt_pk_bf16_f32 v146, v32, v40
	v_cvt_pk_bf16_f32 v147, v48, v56
	global_store_dwordx4 v179, v[144:147], s[16:17]
	v_cvt_pk_bf16_f32 v148, v1, v9
	v_cvt_pk_bf16_f32 v149, v17, v25
	v_cvt_pk_bf16_f32 v150, v33, v41
	v_cvt_pk_bf16_f32 v151, v49, v57
	s_add_u32 s16, s16, s20
	s_addc_u32 s17, s17, 0
	global_store_dwordx4 v179, v[148:151], s[16:17]
	v_cvt_pk_bf16_f32 v152, v2, v10
	v_cvt_pk_bf16_f32 v153, v18, v26
	v_cvt_pk_bf16_f32 v154, v34, v42
	v_cvt_pk_bf16_f32 v155, v50, v58
	s_add_u32 s16, s16, s20
	s_addc_u32 s17, s17, 0
	global_store_dwordx4 v179, v[152:155], s[16:17]
	v_cvt_pk_bf16_f32 v156, v3, v11
	v_cvt_pk_bf16_f32 v157, v19, v27
	v_cvt_pk_bf16_f32 v158, v35, v43
	v_cvt_pk_bf16_f32 v159, v51, v59
	s_add_u32 s16, s16, s20
	s_addc_u32 s17, s17, 0
	global_store_dwordx4 v179, v[156:159], s[16:17]
	s_mov_b64 exec, s[48:49]
	v_cvt_pk_bf16_f32 v160, v4, v12
	v_cvt_pk_bf16_f32 v161, v20, v28
	v_cvt_pk_bf16_f32 v162, v36, v44
	v_cvt_pk_bf16_f32 v163, v52, v60
	s_mul_i32 s2, s20, 29
	s_add_u32 s16, s16, s2
	s_addc_u32 s17, s17, 0
	global_store_dwordx4 v184, v[160:163], s[16:17]
	v_cvt_pk_bf16_f32 v164, v5, v13
	v_cvt_pk_bf16_f32 v165, v21, v29
	v_cvt_pk_bf16_f32 v166, v37, v45
	v_cvt_pk_bf16_f32 v167, v53, v61
	s_add_u32 s16, s16, s20
	s_addc_u32 s17, s17, 0
	global_store_dwordx4 v184, v[164:167], s[16:17]
	v_cvt_pk_bf16_f32 v168, v6, v14
	v_cvt_pk_bf16_f32 v169, v22, v30
	v_cvt_pk_bf16_f32 v170, v38, v46
	v_cvt_pk_bf16_f32 v171, v54, v62
	s_add_u32 s16, s16, s20
	s_addc_u32 s17, s17, 0
	global_store_dwordx4 v184, v[168:171], s[16:17]
	v_cvt_pk_bf16_f32 v172, v7, v15
	v_cvt_pk_bf16_f32 v173, v23, v31
	v_cvt_pk_bf16_f32 v174, v39, v47
	v_cvt_pk_bf16_f32 v175, v55, v63
	s_add_u32 s16, s16, s20
	s_addc_u32 s17, s17, 0
	global_store_dwordx4 v184, v[172:175], s[16:17]
	s_mov_b64 exec, -1
	s_cmp_lt_u32 s4, 0xea4
	s_cbranch_scc1 .Lcv1_la_go
	s_mov_b32 s22, 0
	s_branch .Lcv1_la_end

.Lcv1_pb_plain:
	v_pk_mul_f32 v[64:65], v[64:65], v[136:137] op_sel_hi:[1,0]
	v_pk_mul_f32 v[66:67], v[66:67], v[136:137] op_sel_hi:[1,0]
	v_pk_mul_f32 v[68:69], v[68:69], v[136:137] op_sel_hi:[1,0]
	v_pk_mul_f32 v[70:71], v[70:71], v[136:137] op_sel_hi:[1,0]
	v_pk_mul_f32 v[72:73], v[72:73], v[136:137] op_sel:[0,1]
	v_pk_mul_f32 v[74:75], v[74:75], v[136:137] op_sel:[0,1]
	v_pk_mul_f32 v[76:77], v[76:77], v[136:137] op_sel:[0,1]
	v_pk_mul_f32 v[78:79], v[78:79], v[136:137] op_sel:[0,1]
	v_pk_mul_f32 v[80:81], v[80:81], v[138:139] op_sel_hi:[1,0]
	v_pk_mul_f32 v[82:83], v[82:83], v[138:139] op_sel_hi:[1,0]
	v_pk_mul_f32 v[84:85], v[84:85], v[138:139] op_sel_hi:[1,0]
	v_pk_mul_f32 v[86:87], v[86:87], v[138:139] op_sel_hi:[1,0]
	v_pk_mul_f32 v[88:89], v[88:89], v[138:139] op_sel:[0,1]
	v_pk_mul_f32 v[90:91], v[90:91], v[138:139] op_sel:[0,1]
	v_pk_mul_f32 v[92:93], v[92:93], v[138:139] op_sel:[0,1]
	v_pk_mul_f32 v[94:95], v[94:95], v[138:139] op_sel:[0,1]
	v_pk_mul_f32 v[96:97], v[96:97], v[140:141] op_sel_hi:[1,0]
	v_pk_mul_f32 v[98:99], v[98:99], v[140:141] op_sel_hi:[1,0]
	v_pk_mul_f32 v[100:101], v[100:101], v[140:141] op_sel_hi:[1,0]
	v_pk_mul_f32 v[102:103], v[102:103], v[140:141] op_sel_hi:[1,0]
	v_pk_mul_f32 v[104:105], v[104:105], v[140:141] op_sel:[0,1]
	v_pk_mul_f32 v[106:107], v[106:107], v[140:141] op_sel:[0,1]
	v_pk_mul_f32 v[108:109], v[108:109], v[140:141] op_sel:[0,1]
	v_pk_mul_f32 v[110:111], v[110:111], v[140:141] op_sel:[0,1]
	v_pk_mul_f32 v[112:113], v[112:113], v[142:143] op_sel_hi:[1,0]
	v_pk_mul_f32 v[114:115], v[114:115], v[142:143] op_sel_hi:[1,0]
	v_pk_mul_f32 v[116:117], v[116:117], v[142:143] op_sel_hi:[1,0]
	v_pk_mul_f32 v[118:119], v[118:119], v[142:143] op_sel_hi:[1,0]
	v_pk_mul_f32 v[120:121], v[120:121], v[142:143] op_sel:[0,1]
	v_pk_mul_f32 v[122:123], v[122:123], v[142:143] op_sel:[0,1]
	v_pk_mul_f32 v[124:125], v[124:125], v[142:143] op_sel:[0,1]
	v_pk_mul_f32 v[126:127], v[126:127], v[142:143] op_sel:[0,1]
	v_cvt_pk_bf16_f32 v144, v64, v72
	v_cvt_pk_bf16_f32 v145, v80, v88
	v_cvt_pk_bf16_f32 v146, v96, v104
	v_cvt_pk_bf16_f32 v147, v112, v120
	global_store_dwordx4 v179, v[144:147], s[24:25]
	v_cvt_pk_bf16_f32 v148, v65, v73
	v_cvt_pk_bf16_f32 v149, v81, v89
	v_cvt_pk_bf16_f32 v150, v97, v105
	v_cvt_pk_bf16_f32 v151, v113, v121
	s_add_u32 s24, s24, s26
	s_addc_u32 s25, s25, 0
	global_store_dwordx4 v179, v[148:151], s[24:25]
	v_cvt_pk_bf16_f32 v152, v66, v74
	v_cvt_pk_bf16_f32 v153, v82, v90
	v_cvt_pk_bf16_f32 v154, v98, v106
	v_cvt_pk_bf16_f32 v155, v114, v122
	s_add_u32 s24, s24, s26
	s_addc_u32 s25, s25, 0
	global_store_dwordx4 v179, v[152:155], s[24:25]
	v_cvt_pk_bf16_f32 v156, v67, v75
	v_cvt_pk_bf16_f32 v157, v83, v91
	v_cvt_pk_bf16_f32 v158, v99, v107
	v_cvt_pk_bf16_f32 v159, v115, v123
	s_add_u32 s24, s24, s26
	s_addc_u32 s25, s25, 0
	global_store_dwordx4 v179, v[156:159], s[24:25]
	s_mov_b64 exec, s[48:49]
	v_cvt_pk_bf16_f32 v160, v68, v76
	v_cvt_pk_bf16_f32 v161, v84, v92
	v_cvt_pk_bf16_f32 v162, v100, v108
	v_cvt_pk_bf16_f32 v163, v116, v124
	s_mul_i32 s2, s26, 29
	s_add_u32 s24, s24, s2
	s_addc_u32 s25, s25, 0
	global_store_dwordx4 v184, v[160:163], s[24:25]
	v_cvt_pk_bf16_f32 v164, v69, v77
	v_cvt_pk_bf16_f32 v165, v85, v93
	v_cvt_pk_bf16_f32 v166, v101, v109
	v_cvt_pk_bf16_f32 v167, v117, v125
	s_add_u32 s24, s24, s26
	s_addc_u32 s25, s25, 0
	global_store_dwordx4 v184, v[164:167], s[24:25]
	v_cvt_pk_bf16_f32 v168, v70, v78
	v_cvt_pk_bf16_f32 v169, v86, v94
	v_cvt_pk_bf16_f32 v170, v102, v110
	v_cvt_pk_bf16_f32 v171, v118, v126
	s_add_u32 s24, s24, s26
	s_addc_u32 s25, s25, 0
	global_store_dwordx4 v184, v[168:171], s[24:25]
	v_cvt_pk_bf16_f32 v172, v71, v79
	v_cvt_pk_bf16_f32 v173, v87, v95
	v_cvt_pk_bf16_f32 v174, v103, v111
	v_cvt_pk_bf16_f32 v175, v119, v127
	s_add_u32 s24, s24, s26
	s_addc_u32 s25, s25, 0
	global_store_dwordx4 v184, v[172:175], s[24:25]
	s_mov_b64 exec, -1
	s_cmp_lt_u32 s4, 0xea4
	s_cbranch_scc1 .Lcv1_lb_go
	s_mov_b32 s28, 0
	s_branch .Lcv1_lb_end
